# w_out tiles t<256 moved from P0 (where they cost 32 workgroups a fourth item round) into seam 1, workers 512..767; P0 item count now 6144 = 3 per wave
# speedup vs baseline: 1.0071x; 1.0071x over previous
.LBB0_21:
	s_lshr_b32 s95, s56, 6
	s_add_u32 s56, s26, 0x200000
	s_addc_u32 s57, s27, 0
	s_add_u32 s6, s26, 0x1a00000
	s_addc_u32 s7, s27, 0
	s_add_u32 s52, s26, 0x2200000
	s_addc_u32 s53, s27, 0
	s_add_u32 s58, s26, 0x100000
	s_addc_u32 s59, s27, 0
	s_cmp_lt_i32 s28, 1
	s_cselect_b64 s[0:1], -1, 0
	s_cmp_gt_i32 s29, 0
	s_cselect_b64 s[4:5], -1, 0
	s_and_b64 s[60:61], s[0:1], s[4:5]
	s_andn2_b64 vcc, exec, s[60:61]
	v_and_b32_e32 v209, 63, v208
	s_cbranch_vccnz .LBB0_253
	s_lshl_b32 s0, s3, 3
	s_add_i32 s62, s0, s95
	s_lshl_b32 s64, s30, 3
	s_cmpk_gt_i32 s62, 0x17ff
	s_cbranch_scc1 .LBB0_241
	s_lshl_b32 s0, s95, 14
	v_lshrrev_b32_e32 v76, 5, v209
	v_and_b32_e32 v12, 31, v208
	s_add_i32 s4, s0, 0
	v_lshlrev_b32_e32 v8, 2, v12
	v_mul_u32_u24_e32 v0, 0x84, v76
	s_waitcnt lgkmcnt(0)
	s_cmp_lg_u64 s[16:17], 0
	v_add3_u32 v77, s4, v8, v0
	v_lshlrev_b32_e32 v0, 3, v208
	v_mov_b32_e32 v1, 0
	s_cselect_b64 s[0:1], -1, 0
	v_lshrrev_b32_e32 v78, 3, v209
	v_and_b32_e32 v0, 56, v0
	s_cmp_lg_u64 s[10:11], 0
	v_mul_u32_u24_e32 v4, 0x84, v0
	v_lshlrev_b32_e32 v0, 1, v0
	v_lshlrev_b32_e32 v5, 2, v78
	v_mov_b32_e32 v9, v1
	s_cselect_b64 s[66:67], -1, 0
	s_cmp_lg_u64 s[38:39], 0
	s_mov_b32 s5, 0
	v_lshl_add_u64 v[2:3], s[52:53], 0, v[0:1]
	v_add3_u32 v79, s4, v4, v5
	v_or_b32_e32 v80, 8, v78
	v_or_b32_e32 v81, 16, v78
	v_or_b32_e32 v82, 24, v78
	v_lshl_add_u64 v[4:5], s[14:15], 0, v[8:9]
	v_lshl_add_u64 v[6:7], s[6:7], 0, v[0:1]
	v_lshl_add_u64 v[8:9], s[40:41], 0, v[8:9]
	s_cselect_b64 s[14:15], -1, 0
	v_lshl_add_u64 v[10:11], s[56:57], 0, v[0:1]
	s_lshl_b32 s63, s62, 5
	s_lshl_b32 s65, s64, 5
	s_lshl_b32 s74, s62, 7
	s_lshl_b32 s75, s64, 7
	s_movk_i32 s76, 0xca00
	v_lshlrev_b32_e32 v12, 2, v12
	s_movk_i32 s77, 0x5800
	s_movk_i32 s78, 0x7fff
	s_mov_b32 s79, 0xffff0000
	s_movk_i32 s80, 0x6000
	s_xor_b64 s[40:41], s[0:1], -1
	s_xor_b64 s[66:67], s[66:67], -1
	s_mov_b32 s81, s62
	s_branch .LBB0_26

.LBB0_25:
	s_add_i32 s81, s81, s64
	s_add_i32 s63, s63, s65
	s_add_i32 s74, s74, s75
	s_cmpk_gt_i32 s81, 0x17ff
	s_cbranch_scc1 .LBB0_241

.LBB0_340:
	s_cmp_gt_u32 s29, 2
	s_cselect_b64 s[0:1], -1, 0
	s_and_b64 s[0:1], s[20:21], s[0:1]
	s_andn2_b64 vcc, exec, s[0:1]
	s_cbranch_vccnz .LBB0_392
	s_waitcnt vmcnt(0)
	v_cmp_eq_u32_e32 vcc, 0, v208
	s_waitcnt vmcnt(0) lgkmcnt(0)
	s_barrier
	v_readfirstlane_b32 s3, v208
	s_nop 3
	s_lshr_b32 s3, s3, 6
	s_cmp_eq_u32 s3, 0
	s_cbranch_scc1 .Lmy_cv1_end
	v_readlane_b32 s36, v237, 0
	v_readlane_b32 s37, v237, 1
	s_mul_i32 s4, s2, 7
	s_add_i32 s4, s4, s3
	s_add_i32 s4, s4, -1
	s_lshl_b32 s72, s3, 14
	s_mov_b32 s3, s4
	s_nop 4
	s_load_dwordx4 s[60:63], s[36:37], 0x60
	s_load_dwordx2 s[64:65], s[36:37], 0x70
	s_load_dwordx2 s[98:99], s[36:37], 0x58
	s_load_dwordx2 s[100:101], s[36:37], 0x48
	v_lshrrev_b32_e32 v6, 5, v209
	v_and_b32_e32 v7, 31, v209
	v_mul_u32_u24_e32 v0, 0x1600, v6
	v_add_lshl_u32 v0, v0, v7, 2
	v_lshlrev_b32_e32 v152, 11, v6
	v_add_lshl_u32 v152, v152, v7, 2
	v_mul_u32_u24_e32 v2, 66, v7
	v_add_lshl_u32 v2, v2, v6, 2
	v_add_u32_e32 v2, s72, v2
	v_and_b32_e32 v8, 7, v209
	v_lshrrev_b32_e32 v9, 3, v209
	v_mul_u32_u24_e32 v3, 0x108, v9
	v_lshl_add_u32 v3, v8, 5, v3
	v_add_u32_e32 v3, s72, v3
	v_lshlrev_b32_e32 v4, 12, v9
	v_lshl_add_u32 v4, v8, 4, v4
	v_lshlrev_b32_e32 v5, 5, v8
	s_waitcnt lgkmcnt(0)
	s_cmpk_lt_u32 s3, 0x200
	s_cbranch_scc0 .Lmy_cv1_no3a
	s_mov_b32 s66, s3
	s_cmpk_ge_u32 s66, 0x1600
	s_cselect_b32 s68, s64, s62
	s_cselect_b32 s69, s65, s63
	s_cselect_b32 s41, 0x1600, 0
	s_sub_u32 s41, s66, s41
	s_mul_hi_u32 vcc_lo, s41, 0xba2e8ba3
	s_lshr_b32 vcc_lo, vcc_lo, 7
	s_mul_i32 s70, vcc_lo, 0xb0
	s_sub_u32 vcc_hi, s41, s70
	s_mul_i32 s70, vcc_lo, 0x160000
	s_lshl_b32 s71, vcc_hi, 7
	s_add_u32 s68, s68, s70
	s_addc_u32 s69, s69, 0
	s_add_u32 s68, s68, s71
	s_addc_u32 s69, s69, 0
	v_mov_b32_e32 v1, v0
	global_load_dword v112, v1, s[68:69] nt
	v_add_u32_e32 v1, 0xb000, v1
	global_load_dword v113, v1, s[68:69] nt
	v_add_u32_e32 v1, 0xb000, v1
	global_load_dword v114, v1, s[68:69] nt
	v_add_u32_e32 v1, 0xb000, v1
	global_load_dword v115, v1, s[68:69] nt
	v_add_u32_e32 v1, 0xb000, v1
	global_load_dword v116, v1, s[68:69] nt
	v_add_u32_e32 v1, 0xb000, v1
	global_load_dword v117, v1, s[68:69] nt
	v_add_u32_e32 v1, 0xb000, v1
	global_load_dword v118, v1, s[68:69] nt
	v_add_u32_e32 v1, 0xb000, v1
	global_load_dword v119, v1, s[68:69] nt
	v_add_u32_e32 v1, 0xb000, v1
	global_load_dword v120, v1, s[68:69] nt
	v_add_u32_e32 v1, 0xb000, v1
	global_load_dword v121, v1, s[68:69] nt
	v_add_u32_e32 v1, 0xb000, v1
	global_load_dword v122, v1, s[68:69] nt
	v_add_u32_e32 v1, 0xb000, v1
	global_load_dword v123, v1, s[68:69] nt
	v_add_u32_e32 v1, 0xb000, v1
	global_load_dword v124, v1, s[68:69] nt
	v_add_u32_e32 v1, 0xb000, v1
	global_load_dword v125, v1, s[68:69] nt
	v_add_u32_e32 v1, 0xb000, v1
	global_load_dword v126, v1, s[68:69] nt
	v_add_u32_e32 v1, 0xb000, v1
	global_load_dword v127, v1, s[68:69] nt
	v_add_u32_e32 v1, 0xb000, v1
	global_load_dword v128, v1, s[68:69] nt
	v_add_u32_e32 v1, 0xb000, v1
	global_load_dword v129, v1, s[68:69] nt
	v_add_u32_e32 v1, 0xb000, v1
	global_load_dword v130, v1, s[68:69] nt
	v_add_u32_e32 v1, 0xb000, v1
	global_load_dword v131, v1, s[68:69] nt
	v_add_u32_e32 v1, 0xb000, v1
	global_load_dword v132, v1, s[68:69] nt
	v_add_u32_e32 v1, 0xb000, v1
	global_load_dword v133, v1, s[68:69] nt
	v_add_u32_e32 v1, 0xb000, v1
	global_load_dword v134, v1, s[68:69] nt
	v_add_u32_e32 v1, 0xb000, v1
	global_load_dword v135, v1, s[68:69] nt
	v_add_u32_e32 v1, 0xb000, v1
	global_load_dword v136, v1, s[68:69] nt
	v_add_u32_e32 v1, 0xb000, v1
	global_load_dword v137, v1, s[68:69] nt
	v_add_u32_e32 v1, 0xb000, v1
	global_load_dword v138, v1, s[68:69] nt
	v_add_u32_e32 v1, 0xb000, v1
	global_load_dword v139, v1, s[68:69] nt
	v_add_u32_e32 v1, 0xb000, v1
	global_load_dword v140, v1, s[68:69] nt
	v_add_u32_e32 v1, 0xb000, v1
	global_load_dword v141, v1, s[68:69] nt
	v_add_u32_e32 v1, 0xb000, v1
	global_load_dword v142, v1, s[68:69] nt
	v_add_u32_e32 v1, 0xb000, v1
	global_load_dword v143, v1, s[68:69] nt
	s_lshl_b32 s70, vcc_lo, 8
	s_add_u32 s70, s60, s70
	s_addc_u32 s71, s61, 0
	global_load_dwordx4 v[144:147], v5, s[70:71]
	global_load_dwordx4 v[148:151], v5, s[70:71] offset:16
	s_branch .Lmy_cv1_dn3a
.Lmy_cv1_no3a:
	s_cmpk_lt_u32 s3, 0x300
	s_cbranch_scc0 .Lmy_cv1_dn3a
	s_add_i32 s66, s3, 0xfffffe00
	s_lshr_b32 vcc_lo, s66, 6
	s_and_b32 vcc_hi, s66, 63
	s_lshl_b32 s70, vcc_lo, 19
	s_lshl_b32 s71, vcc_hi, 7
	s_add_u32 s68, s98, s70
	s_addc_u32 s69, s99, 0
	s_add_u32 s68, s68, s71
	s_addc_u32 s69, s69, 0
	v_mov_b32_e32 v1, v152
	global_load_dword v112, v1, s[68:69] nt
	v_add_u32_e32 v1, 0x4000, v1
	global_load_dword v113, v1, s[68:69] nt
	v_add_u32_e32 v1, 0x4000, v1
	global_load_dword v114, v1, s[68:69] nt
	v_add_u32_e32 v1, 0x4000, v1
	global_load_dword v115, v1, s[68:69] nt
	v_add_u32_e32 v1, 0x4000, v1
	global_load_dword v116, v1, s[68:69] nt
	v_add_u32_e32 v1, 0x4000, v1
	global_load_dword v117, v1, s[68:69] nt
	v_add_u32_e32 v1, 0x4000, v1
	global_load_dword v118, v1, s[68:69] nt
	v_add_u32_e32 v1, 0x4000, v1
	global_load_dword v119, v1, s[68:69] nt
	v_add_u32_e32 v1, 0x4000, v1
	global_load_dword v120, v1, s[68:69] nt
	v_add_u32_e32 v1, 0x4000, v1
	global_load_dword v121, v1, s[68:69] nt
	v_add_u32_e32 v1, 0x4000, v1
	global_load_dword v122, v1, s[68:69] nt
	v_add_u32_e32 v1, 0x4000, v1
	global_load_dword v123, v1, s[68:69] nt
	v_add_u32_e32 v1, 0x4000, v1
	global_load_dword v124, v1, s[68:69] nt
	v_add_u32_e32 v1, 0x4000, v1
	global_load_dword v125, v1, s[68:69] nt
	v_add_u32_e32 v1, 0x4000, v1
	global_load_dword v126, v1, s[68:69] nt
	v_add_u32_e32 v1, 0x4000, v1
	global_load_dword v127, v1, s[68:69] nt
	v_add_u32_e32 v1, 0x4000, v1
	global_load_dword v128, v1, s[68:69] nt
	v_add_u32_e32 v1, 0x4000, v1
	global_load_dword v129, v1, s[68:69] nt
	v_add_u32_e32 v1, 0x4000, v1
	global_load_dword v130, v1, s[68:69] nt
	v_add_u32_e32 v1, 0x4000, v1
	global_load_dword v131, v1, s[68:69] nt
	v_add_u32_e32 v1, 0x4000, v1
	global_load_dword v132, v1, s[68:69] nt
	v_add_u32_e32 v1, 0x4000, v1
	global_load_dword v133, v1, s[68:69] nt
	v_add_u32_e32 v1, 0x4000, v1
	global_load_dword v134, v1, s[68:69] nt
	v_add_u32_e32 v1, 0x4000, v1
	global_load_dword v135, v1, s[68:69] nt
	v_add_u32_e32 v1, 0x4000, v1
	global_load_dword v136, v1, s[68:69] nt
	v_add_u32_e32 v1, 0x4000, v1
	global_load_dword v137, v1, s[68:69] nt
	v_add_u32_e32 v1, 0x4000, v1
	global_load_dword v138, v1, s[68:69] nt
	v_add_u32_e32 v1, 0x4000, v1
	global_load_dword v139, v1, s[68:69] nt
	v_add_u32_e32 v1, 0x4000, v1
	global_load_dword v140, v1, s[68:69] nt
	v_add_u32_e32 v1, 0x4000, v1
	global_load_dword v141, v1, s[68:69] nt
	v_add_u32_e32 v1, 0x4000, v1
	global_load_dword v142, v1, s[68:69] nt
	v_add_u32_e32 v1, 0x4000, v1
	global_load_dword v143, v1, s[68:69] nt
	s_and_b32 s70, vcc_lo, 1
	s_lshl_b32 s70, s70, 8
	s_add_u32 s70, s100, s70
	s_addc_u32 s71, s101, 0
	global_load_dwordx4 v[144:147], v5, s[70:71]
	global_load_dwordx4 v[148:151], v5, s[70:71] offset:16
.Lmy_cv1_dn3a:
	s_add_i32 s66, s3, 4096
	s_cmpk_ge_u32 s66, 0x1600
	s_cselect_b32 s68, s64, s62
	s_cselect_b32 s69, s65, s63
	s_cselect_b32 s54, 128, 0
	s_cselect_b32 s41, 0x1600, 0
	s_sub_u32 s41, s66, s41
	s_mul_hi_u32 s4, s41, 0xba2e8ba3
	s_lshr_b32 s4, s4, 7
	s_mul_i32 s70, s4, 0xb0
	s_sub_u32 s5, s41, s70
	s_mul_i32 s70, s4, 0x160000
	s_lshl_b32 s71, s5, 7
	s_add_u32 s68, s68, s70
	s_addc_u32 s69, s69, 0
	s_add_u32 s68, s68, s71
	s_addc_u32 s69, s69, 0
	v_mov_b32_e32 v1, v0
	global_load_dword v32, v1, s[68:69] nt
	v_add_u32_e32 v1, 0xb000, v1
	global_load_dword v33, v1, s[68:69] nt
	v_add_u32_e32 v1, 0xb000, v1
	global_load_dword v34, v1, s[68:69] nt
	v_add_u32_e32 v1, 0xb000, v1
	global_load_dword v35, v1, s[68:69] nt
	v_add_u32_e32 v1, 0xb000, v1
	global_load_dword v36, v1, s[68:69] nt
	v_add_u32_e32 v1, 0xb000, v1
	global_load_dword v37, v1, s[68:69] nt
	v_add_u32_e32 v1, 0xb000, v1
	global_load_dword v38, v1, s[68:69] nt
	v_add_u32_e32 v1, 0xb000, v1
	global_load_dword v39, v1, s[68:69] nt
	v_add_u32_e32 v1, 0xb000, v1
	global_load_dword v40, v1, s[68:69] nt
	v_add_u32_e32 v1, 0xb000, v1
	global_load_dword v41, v1, s[68:69] nt
	v_add_u32_e32 v1, 0xb000, v1
	global_load_dword v42, v1, s[68:69] nt
	v_add_u32_e32 v1, 0xb000, v1
	global_load_dword v43, v1, s[68:69] nt
	v_add_u32_e32 v1, 0xb000, v1
	global_load_dword v44, v1, s[68:69] nt
	v_add_u32_e32 v1, 0xb000, v1
	global_load_dword v45, v1, s[68:69] nt
	v_add_u32_e32 v1, 0xb000, v1
	global_load_dword v46, v1, s[68:69] nt
	v_add_u32_e32 v1, 0xb000, v1
	global_load_dword v47, v1, s[68:69] nt
	v_add_u32_e32 v1, 0xb000, v1
	global_load_dword v48, v1, s[68:69] nt
	v_add_u32_e32 v1, 0xb000, v1
	global_load_dword v49, v1, s[68:69] nt
	v_add_u32_e32 v1, 0xb000, v1
	global_load_dword v50, v1, s[68:69] nt
	v_add_u32_e32 v1, 0xb000, v1
	global_load_dword v51, v1, s[68:69] nt
	v_add_u32_e32 v1, 0xb000, v1
	global_load_dword v52, v1, s[68:69] nt
	v_add_u32_e32 v1, 0xb000, v1
	global_load_dword v53, v1, s[68:69] nt
	v_add_u32_e32 v1, 0xb000, v1
	global_load_dword v54, v1, s[68:69] nt
	v_add_u32_e32 v1, 0xb000, v1
	global_load_dword v55, v1, s[68:69] nt
	v_add_u32_e32 v1, 0xb000, v1
	global_load_dword v56, v1, s[68:69] nt
	v_add_u32_e32 v1, 0xb000, v1
	global_load_dword v57, v1, s[68:69] nt
	v_add_u32_e32 v1, 0xb000, v1
	global_load_dword v58, v1, s[68:69] nt
	v_add_u32_e32 v1, 0xb000, v1
	global_load_dword v59, v1, s[68:69] nt
	v_add_u32_e32 v1, 0xb000, v1
	global_load_dword v60, v1, s[68:69] nt
	v_add_u32_e32 v1, 0xb000, v1
	global_load_dword v61, v1, s[68:69] nt
	v_add_u32_e32 v1, 0xb000, v1
	global_load_dword v62, v1, s[68:69] nt
	v_add_u32_e32 v1, 0xb000, v1
	global_load_dword v63, v1, s[68:69] nt
	s_lshl_b32 s70, s4, 8
	s_add_u32 s70, s60, s70
	s_addc_u32 s71, s61, 0
	global_load_dwordx4 v[96:99], v5, s[70:71]
	global_load_dwordx4 v[100:103], v5, s[70:71] offset:16
	s_addk_i32 s66, 0x700
	s_cmpk_ge_u32 s66, 0x1600
	s_cselect_b32 s68, s64, s62
	s_cselect_b32 s69, s65, s63
	s_cselect_b32 s40, 128, 0
	s_cselect_b32 s41, 0x1600, 0
	s_sub_u32 s41, s66, s41
	s_mul_hi_u32 s55, s41, 0xba2e8ba3
	s_lshr_b32 s55, s55, 7
	s_mul_i32 s70, s55, 0xb0
	s_sub_u32 s67, s41, s70
	s_mul_i32 s70, s55, 0x160000
	s_lshl_b32 s71, s67, 7
	s_add_u32 s68, s68, s70
	s_addc_u32 s69, s69, 0
	s_add_u32 s68, s68, s71
	s_addc_u32 s69, s69, 0
	v_mov_b32_e32 v1, v0
	global_load_dword v64, v1, s[68:69] nt
	v_add_u32_e32 v1, 0xb000, v1
	global_load_dword v65, v1, s[68:69] nt
	v_add_u32_e32 v1, 0xb000, v1
	global_load_dword v66, v1, s[68:69] nt
	v_add_u32_e32 v1, 0xb000, v1
	global_load_dword v67, v1, s[68:69] nt
	v_add_u32_e32 v1, 0xb000, v1
	global_load_dword v68, v1, s[68:69] nt
	v_add_u32_e32 v1, 0xb000, v1
	global_load_dword v69, v1, s[68:69] nt
	v_add_u32_e32 v1, 0xb000, v1
	global_load_dword v70, v1, s[68:69] nt
	v_add_u32_e32 v1, 0xb000, v1
	global_load_dword v71, v1, s[68:69] nt
	v_add_u32_e32 v1, 0xb000, v1
	global_load_dword v72, v1, s[68:69] nt
	v_add_u32_e32 v1, 0xb000, v1
	global_load_dword v73, v1, s[68:69] nt
	v_add_u32_e32 v1, 0xb000, v1
	global_load_dword v74, v1, s[68:69] nt
	v_add_u32_e32 v1, 0xb000, v1
	global_load_dword v75, v1, s[68:69] nt
	v_add_u32_e32 v1, 0xb000, v1
	global_load_dword v76, v1, s[68:69] nt
	v_add_u32_e32 v1, 0xb000, v1
	global_load_dword v77, v1, s[68:69] nt
	v_add_u32_e32 v1, 0xb000, v1
	global_load_dword v78, v1, s[68:69] nt
	v_add_u32_e32 v1, 0xb000, v1
	global_load_dword v79, v1, s[68:69] nt
	v_add_u32_e32 v1, 0xb000, v1
	global_load_dword v80, v1, s[68:69] nt
	v_add_u32_e32 v1, 0xb000, v1
	global_load_dword v81, v1, s[68:69] nt
	v_add_u32_e32 v1, 0xb000, v1
	global_load_dword v82, v1, s[68:69] nt
	v_add_u32_e32 v1, 0xb000, v1
	global_load_dword v83, v1, s[68:69] nt
	v_add_u32_e32 v1, 0xb000, v1
	global_load_dword v84, v1, s[68:69] nt
	v_add_u32_e32 v1, 0xb000, v1
	global_load_dword v85, v1, s[68:69] nt
	v_add_u32_e32 v1, 0xb000, v1
	global_load_dword v86, v1, s[68:69] nt
	v_add_u32_e32 v1, 0xb000, v1
	global_load_dword v87, v1, s[68:69] nt
	v_add_u32_e32 v1, 0xb000, v1
	global_load_dword v88, v1, s[68:69] nt
	v_add_u32_e32 v1, 0xb000, v1
	global_load_dword v89, v1, s[68:69] nt
	v_add_u32_e32 v1, 0xb000, v1
	global_load_dword v90, v1, s[68:69] nt
	v_add_u32_e32 v1, 0xb000, v1
	global_load_dword v91, v1, s[68:69] nt
	v_add_u32_e32 v1, 0xb000, v1
	global_load_dword v92, v1, s[68:69] nt
	v_add_u32_e32 v1, 0xb000, v1
	global_load_dword v93, v1, s[68:69] nt
	v_add_u32_e32 v1, 0xb000, v1
	global_load_dword v94, v1, s[68:69] nt
	v_add_u32_e32 v1, 0xb000, v1
	global_load_dword v95, v1, s[68:69] nt
	s_lshl_b32 s70, s55, 8
	s_add_u32 s70, s60, s70
	s_addc_u32 s71, s61, 0
	global_load_dwordx4 v[104:107], v5, s[70:71]
	global_load_dwordx4 v[108:111], v5, s[70:71] offset:16
	s_cmpk_lt_u32 s3, 0x200
	s_cbranch_scc0 .Lmy_cv1_no3b
	s_waitcnt vmcnt(63)
	s_waitcnt lgkmcnt(0)
	ds_write_b32 v2, v112 offset:0
	ds_write_b32 v2, v113 offset:8
	ds_write_b32 v2, v114 offset:16
	ds_write_b32 v2, v115 offset:24
	ds_write_b32 v2, v116 offset:32
	ds_write_b32 v2, v117 offset:40
	ds_write_b32 v2, v118 offset:48
	ds_write_b32 v2, v119 offset:56
	ds_write_b32 v2, v120 offset:64
	ds_write_b32 v2, v121 offset:72
	ds_write_b32 v2, v122 offset:80
	ds_write_b32 v2, v123 offset:88
	ds_write_b32 v2, v124 offset:96
	ds_write_b32 v2, v125 offset:104
	ds_write_b32 v2, v126 offset:112
	ds_write_b32 v2, v127 offset:120
	ds_write_b32 v2, v128 offset:128
	ds_write_b32 v2, v129 offset:136
	ds_write_b32 v2, v130 offset:144
	ds_write_b32 v2, v131 offset:152
	ds_write_b32 v2, v132 offset:160
	ds_write_b32 v2, v133 offset:168
	ds_write_b32 v2, v134 offset:176
	ds_write_b32 v2, v135 offset:184
	ds_write_b32 v2, v136 offset:192
	ds_write_b32 v2, v137 offset:200
	ds_write_b32 v2, v138 offset:208
	ds_write_b32 v2, v139 offset:216
	ds_write_b32 v2, v140 offset:224
	ds_write_b32 v2, v141 offset:232
	ds_write_b32 v2, v142 offset:240
	ds_write_b32 v2, v143 offset:248
	s_lshr_b32 s70, vcc_hi, 2
	s_lshl_b32 s70, s70, 8
	s_and_b32 s71, vcc_hi, 3
	s_lshl_b32 s71, s71, 5
	s_add_i32 s70, s70, s71
	s_lshl_b32 s70, s70, 12
	s_lshl_b32 s71, vcc_lo, 7
	s_add_i32 s70, s70, s71
	s_add_u32 s70, s70, 0x2200000
	s_add_u32 s70, s26, s70
	s_addc_u32 s71, s27, 0
	s_waitcnt lgkmcnt(0)
	ds_read_b64 v[160:161], v3 offset:0
	ds_read_b64 v[162:163], v3 offset:8
	ds_read_b64 v[164:165], v3 offset:16
	ds_read_b64 v[166:167], v3 offset:24
	ds_read_b64 v[168:169], v3 offset:2112
	ds_read_b64 v[170:171], v3 offset:2120
	ds_read_b64 v[172:173], v3 offset:2128
	ds_read_b64 v[174:175], v3 offset:2136
	ds_read_b64 v[176:177], v3 offset:4224
	ds_read_b64 v[178:179], v3 offset:4232
	ds_read_b64 v[180:181], v3 offset:4240
	ds_read_b64 v[182:183], v3 offset:4248
	ds_read_b64 v[184:185], v3 offset:6336
	ds_read_b64 v[186:187], v3 offset:6344
	ds_read_b64 v[188:189], v3 offset:6352
	ds_read_b64 v[190:191], v3 offset:6360
	s_waitcnt lgkmcnt(12)
	v_mul_f32_e32 v160, v160, v144
	v_mul_f32_e32 v161, v161, v145
	v_mul_f32_e32 v162, v162, v146
	v_mul_f32_e32 v163, v163, v147
	v_mul_f32_e32 v164, v164, v148
	v_mul_f32_e32 v165, v165, v149
	v_mul_f32_e32 v166, v166, v150
	v_mul_f32_e32 v167, v167, v151
	v_cvt_pk_bf16_f32 v192, v160, v161
	v_cvt_pk_bf16_f32 v193, v162, v163
	v_cvt_pk_bf16_f32 v194, v164, v165
	v_cvt_pk_bf16_f32 v195, v166, v167
	v_mov_b32_e32 v9, v4
	global_store_dwordx4 v9, v[192:195], s[70:71]
	s_waitcnt lgkmcnt(8)
	v_mul_f32_e32 v168, v168, v144
	v_mul_f32_e32 v169, v169, v145
	v_mul_f32_e32 v170, v170, v146
	v_mul_f32_e32 v171, v171, v147
	v_mul_f32_e32 v172, v172, v148
	v_mul_f32_e32 v173, v173, v149
	v_mul_f32_e32 v174, v174, v150
	v_mul_f32_e32 v175, v175, v151
	v_cvt_pk_bf16_f32 v196, v168, v169
	v_cvt_pk_bf16_f32 v197, v170, v171
	v_cvt_pk_bf16_f32 v198, v172, v173
	v_cvt_pk_bf16_f32 v199, v174, v175
	v_add_u32_e32 v9, 0x8000, v9
	global_store_dwordx4 v9, v[196:199], s[70:71]
	s_waitcnt lgkmcnt(4)
	v_mul_f32_e32 v176, v176, v144
	v_mul_f32_e32 v177, v177, v145
	v_mul_f32_e32 v178, v178, v146
	v_mul_f32_e32 v179, v179, v147
	v_mul_f32_e32 v180, v180, v148
	v_mul_f32_e32 v181, v181, v149
	v_mul_f32_e32 v182, v182, v150
	v_mul_f32_e32 v183, v183, v151
	v_cvt_pk_bf16_f32 v200, v176, v177
	v_cvt_pk_bf16_f32 v201, v178, v179
	v_cvt_pk_bf16_f32 v202, v180, v181
	v_cvt_pk_bf16_f32 v203, v182, v183
	v_add_u32_e32 v9, 0x8000, v9
	global_store_dwordx4 v9, v[200:203], s[70:71]
	s_waitcnt lgkmcnt(0)
	v_mul_f32_e32 v184, v184, v144
	v_mul_f32_e32 v185, v185, v145
	v_mul_f32_e32 v186, v186, v146
	v_mul_f32_e32 v187, v187, v147
	v_mul_f32_e32 v188, v188, v148
	v_mul_f32_e32 v189, v189, v149
	v_mul_f32_e32 v190, v190, v150
	v_mul_f32_e32 v191, v191, v151
	v_cvt_pk_bf16_f32 v204, v184, v185
	v_cvt_pk_bf16_f32 v205, v186, v187
	v_cvt_pk_bf16_f32 v206, v188, v189
	v_cvt_pk_bf16_f32 v207, v190, v191
	v_add_u32_e32 v9, 0x8000, v9
	global_store_dwordx4 v9, v[204:207], s[70:71]
	s_branch .Lmy_cv1_dn3b
.Lmy_cv1_no3b:
	s_cmpk_lt_u32 s3, 0x300
	s_cbranch_scc0 .Lmy_cv1_dn3b
	s_waitcnt vmcnt(63)
	s_waitcnt lgkmcnt(0)
	ds_write_b32 v2, v112 offset:0
	ds_write_b32 v2, v113 offset:8
	ds_write_b32 v2, v114 offset:16
	ds_write_b32 v2, v115 offset:24
	ds_write_b32 v2, v116 offset:32
	ds_write_b32 v2, v117 offset:40
	ds_write_b32 v2, v118 offset:48
	ds_write_b32 v2, v119 offset:56
	ds_write_b32 v2, v120 offset:64
	ds_write_b32 v2, v121 offset:72
	ds_write_b32 v2, v122 offset:80
	ds_write_b32 v2, v123 offset:88
	ds_write_b32 v2, v124 offset:96
	ds_write_b32 v2, v125 offset:104
	ds_write_b32 v2, v126 offset:112
	ds_write_b32 v2, v127 offset:120
	ds_write_b32 v2, v128 offset:128
	ds_write_b32 v2, v129 offset:136
	ds_write_b32 v2, v130 offset:144
	ds_write_b32 v2, v131 offset:152
	ds_write_b32 v2, v132 offset:160
	ds_write_b32 v2, v133 offset:168
	ds_write_b32 v2, v134 offset:176
	ds_write_b32 v2, v135 offset:184
	ds_write_b32 v2, v136 offset:192
	ds_write_b32 v2, v137 offset:200
	ds_write_b32 v2, v138 offset:208
	ds_write_b32 v2, v139 offset:216
	ds_write_b32 v2, v140 offset:224
	ds_write_b32 v2, v141 offset:232
	ds_write_b32 v2, v142 offset:240
	ds_write_b32 v2, v143 offset:248
	s_cmp_lt_u32 vcc_lo, 16
	s_cbranch_scc0 .Lmy_cv1_nsx
	v_mul_f32_e32 v144, 0x3f4ccccd, v144
	v_mul_f32_e32 v145, 0x3f4ccccd, v145
	v_mul_f32_e32 v146, 0x3f4ccccd, v146
	v_mul_f32_e32 v147, 0x3f4ccccd, v147
	v_mul_f32_e32 v148, 0x3f4ccccd, v148
	v_mul_f32_e32 v149, 0x3f4ccccd, v149
	v_mul_f32_e32 v150, 0x3f4ccccd, v150
	v_mul_f32_e32 v151, 0x3f4ccccd, v151
	s_branch .Lmy_cv1_sdx

.Lmy_cv1_sdx:
	s_lshl_b32 s70, vcc_hi, 17
	s_lshl_b32 s71, vcc_lo, 7
	s_add_i32 s70, s70, s71
	s_add_u32 s70, s70, 0x1a00000
	s_add_u32 s70, s26, s70
	s_addc_u32 s71, s27, 0
	s_waitcnt lgkmcnt(0)
	ds_read_b64 v[160:161], v3 offset:0
	ds_read_b64 v[162:163], v3 offset:8
	ds_read_b64 v[164:165], v3 offset:16
	ds_read_b64 v[166:167], v3 offset:24
	ds_read_b64 v[168:169], v3 offset:2112
	ds_read_b64 v[170:171], v3 offset:2120
	ds_read_b64 v[172:173], v3 offset:2128
	ds_read_b64 v[174:175], v3 offset:2136
	ds_read_b64 v[176:177], v3 offset:4224
	ds_read_b64 v[178:179], v3 offset:4232
	ds_read_b64 v[180:181], v3 offset:4240
	ds_read_b64 v[182:183], v3 offset:4248
	ds_read_b64 v[184:185], v3 offset:6336
	ds_read_b64 v[186:187], v3 offset:6344
	ds_read_b64 v[188:189], v3 offset:6352
	ds_read_b64 v[190:191], v3 offset:6360
	s_waitcnt lgkmcnt(12)
	v_mul_f32_e32 v160, v160, v144
	v_mul_f32_e32 v161, v161, v145
	v_mul_f32_e32 v162, v162, v146
	v_mul_f32_e32 v163, v163, v147
	v_mul_f32_e32 v164, v164, v148
	v_mul_f32_e32 v165, v165, v149
	v_mul_f32_e32 v166, v166, v150
	v_mul_f32_e32 v167, v167, v151
	v_cvt_pk_bf16_f32 v192, v160, v161
	v_cvt_pk_bf16_f32 v193, v162, v163
	v_cvt_pk_bf16_f32 v194, v164, v165
	v_cvt_pk_bf16_f32 v195, v166, v167
	v_mov_b32_e32 v9, v4
	global_store_dwordx4 v9, v[192:195], s[70:71]
	s_waitcnt lgkmcnt(8)
	v_mul_f32_e32 v168, v168, v144
	v_mul_f32_e32 v169, v169, v145
	v_mul_f32_e32 v170, v170, v146
	v_mul_f32_e32 v171, v171, v147
	v_mul_f32_e32 v172, v172, v148
	v_mul_f32_e32 v173, v173, v149
	v_mul_f32_e32 v174, v174, v150
	v_mul_f32_e32 v175, v175, v151
	v_cvt_pk_bf16_f32 v196, v168, v169
	v_cvt_pk_bf16_f32 v197, v170, v171
	v_cvt_pk_bf16_f32 v198, v172, v173
	v_cvt_pk_bf16_f32 v199, v174, v175
	v_add_u32_e32 v9, 0x8000, v9
	global_store_dwordx4 v9, v[196:199], s[70:71]
	s_waitcnt lgkmcnt(4)
	v_mul_f32_e32 v176, v176, v144
	v_mul_f32_e32 v177, v177, v145
	v_mul_f32_e32 v178, v178, v146
	v_mul_f32_e32 v179, v179, v147
	v_mul_f32_e32 v180, v180, v148
	v_mul_f32_e32 v181, v181, v149
	v_mul_f32_e32 v182, v182, v150
	v_mul_f32_e32 v183, v183, v151
	v_cvt_pk_bf16_f32 v200, v176, v177
	v_cvt_pk_bf16_f32 v201, v178, v179
	v_cvt_pk_bf16_f32 v202, v180, v181
	v_cvt_pk_bf16_f32 v203, v182, v183
	v_add_u32_e32 v9, 0x8000, v9
	global_store_dwordx4 v9, v[200:203], s[70:71]
	s_waitcnt lgkmcnt(0)
	v_mul_f32_e32 v184, v184, v144
	v_mul_f32_e32 v185, v185, v145
	v_mul_f32_e32 v186, v186, v146
	v_mul_f32_e32 v187, v187, v147
	v_mul_f32_e32 v188, v188, v148
	v_mul_f32_e32 v189, v189, v149
	v_mul_f32_e32 v190, v190, v150
	v_mul_f32_e32 v191, v191, v151
	v_cvt_pk_bf16_f32 v204, v184, v185
	v_cvt_pk_bf16_f32 v205, v186, v187
	v_cvt_pk_bf16_f32 v206, v188, v189
	v_cvt_pk_bf16_f32 v207, v190, v191
	v_add_u32_e32 v9, 0x8000, v9
	global_store_dwordx4 v9, v[204:207], s[70:71]
.Lmy_cv1_dn3b:
	s_waitcnt vmcnt(34)
	s_waitcnt lgkmcnt(0)
	ds_write_b32 v2, v32 offset:0
	ds_write_b32 v2, v33 offset:8
	ds_write_b32 v2, v34 offset:16
	ds_write_b32 v2, v35 offset:24
	ds_write_b32 v2, v36 offset:32
	ds_write_b32 v2, v37 offset:40
	ds_write_b32 v2, v38 offset:48
	ds_write_b32 v2, v39 offset:56
	ds_write_b32 v2, v40 offset:64
	ds_write_b32 v2, v41 offset:72
	ds_write_b32 v2, v42 offset:80
	ds_write_b32 v2, v43 offset:88
	ds_write_b32 v2, v44 offset:96
	ds_write_b32 v2, v45 offset:104
	ds_write_b32 v2, v46 offset:112
	ds_write_b32 v2, v47 offset:120
	ds_write_b32 v2, v48 offset:128
	ds_write_b32 v2, v49 offset:136
	ds_write_b32 v2, v50 offset:144
	ds_write_b32 v2, v51 offset:152
	ds_write_b32 v2, v52 offset:160
	ds_write_b32 v2, v53 offset:168
	ds_write_b32 v2, v54 offset:176
	ds_write_b32 v2, v55 offset:184
	ds_write_b32 v2, v56 offset:192
	ds_write_b32 v2, v57 offset:200
	ds_write_b32 v2, v58 offset:208
	ds_write_b32 v2, v59 offset:216
	ds_write_b32 v2, v60 offset:224
	ds_write_b32 v2, v61 offset:232
	ds_write_b32 v2, v62 offset:240
	ds_write_b32 v2, v63 offset:248
	s_lshr_b32 s70, s5, 2
	s_lshl_b32 s70, s70, 8
	s_and_b32 s71, s5, 3
	s_lshl_b32 s71, s71, 5
	s_add_i32 s70, s70, s71
	s_add_i32 s70, s70, s54
	s_lshl_b32 s70, s70, 12
	s_lshl_b32 s71, s4, 7
	s_add_i32 s70, s70, s71
	s_add_u32 s70, s70, 0x2200000
	s_add_u32 s70, s26, s70
	s_addc_u32 s71, s27, 0
	s_waitcnt lgkmcnt(0)
	ds_read_b64 v[160:161], v3 offset:0
	ds_read_b64 v[162:163], v3 offset:8
	ds_read_b64 v[164:165], v3 offset:16
	ds_read_b64 v[166:167], v3 offset:24
	ds_read_b64 v[168:169], v3 offset:2112
	ds_read_b64 v[170:171], v3 offset:2120
	ds_read_b64 v[172:173], v3 offset:2128
	ds_read_b64 v[174:175], v3 offset:2136
	ds_read_b64 v[176:177], v3 offset:4224
	ds_read_b64 v[178:179], v3 offset:4232
	ds_read_b64 v[180:181], v3 offset:4240
	ds_read_b64 v[182:183], v3 offset:4248
	ds_read_b64 v[184:185], v3 offset:6336
	ds_read_b64 v[186:187], v3 offset:6344
	ds_read_b64 v[188:189], v3 offset:6352
	ds_read_b64 v[190:191], v3 offset:6360
	s_waitcnt lgkmcnt(12)
	v_mul_f32_e32 v160, v160, v96
	v_mul_f32_e32 v161, v161, v97
	v_mul_f32_e32 v162, v162, v98
	v_mul_f32_e32 v163, v163, v99
	v_mul_f32_e32 v164, v164, v100
	v_mul_f32_e32 v165, v165, v101
	v_mul_f32_e32 v166, v166, v102
	v_mul_f32_e32 v167, v167, v103
	v_cvt_pk_bf16_f32 v192, v160, v161
	v_cvt_pk_bf16_f32 v193, v162, v163
	v_cvt_pk_bf16_f32 v194, v164, v165
	v_cvt_pk_bf16_f32 v195, v166, v167
	v_mov_b32_e32 v9, v4
	global_store_dwordx4 v9, v[192:195], s[70:71]
	s_waitcnt lgkmcnt(8)
	v_mul_f32_e32 v168, v168, v96
	v_mul_f32_e32 v169, v169, v97
	v_mul_f32_e32 v170, v170, v98
	v_mul_f32_e32 v171, v171, v99
	v_mul_f32_e32 v172, v172, v100
	v_mul_f32_e32 v173, v173, v101
	v_mul_f32_e32 v174, v174, v102
	v_mul_f32_e32 v175, v175, v103
	v_cvt_pk_bf16_f32 v196, v168, v169
	v_cvt_pk_bf16_f32 v197, v170, v171
	v_cvt_pk_bf16_f32 v198, v172, v173
	v_cvt_pk_bf16_f32 v199, v174, v175
	v_add_u32_e32 v9, 0x8000, v9
	global_store_dwordx4 v9, v[196:199], s[70:71]
	s_waitcnt lgkmcnt(4)
	v_mul_f32_e32 v176, v176, v96
	v_mul_f32_e32 v177, v177, v97
	v_mul_f32_e32 v178, v178, v98
	v_mul_f32_e32 v179, v179, v99
	v_mul_f32_e32 v180, v180, v100
	v_mul_f32_e32 v181, v181, v101
	v_mul_f32_e32 v182, v182, v102
	v_mul_f32_e32 v183, v183, v103
	v_cvt_pk_bf16_f32 v200, v176, v177
	v_cvt_pk_bf16_f32 v201, v178, v179
	v_cvt_pk_bf16_f32 v202, v180, v181
	v_cvt_pk_bf16_f32 v203, v182, v183
	v_add_u32_e32 v9, 0x8000, v9
	global_store_dwordx4 v9, v[200:203], s[70:71]
	s_waitcnt lgkmcnt(0)
	v_mul_f32_e32 v184, v184, v96
	v_mul_f32_e32 v185, v185, v97
	v_mul_f32_e32 v186, v186, v98
	v_mul_f32_e32 v187, v187, v99
	v_mul_f32_e32 v188, v188, v100
	v_mul_f32_e32 v189, v189, v101
	v_mul_f32_e32 v190, v190, v102
	v_mul_f32_e32 v191, v191, v103
	v_cvt_pk_bf16_f32 v204, v184, v185
	v_cvt_pk_bf16_f32 v205, v186, v187
	v_cvt_pk_bf16_f32 v206, v188, v189
	v_cvt_pk_bf16_f32 v207, v190, v191
	v_add_u32_e32 v9, 0x8000, v9
	global_store_dwordx4 v9, v[204:207], s[70:71]
	s_waitcnt vmcnt(0)
	s_waitcnt lgkmcnt(0)
	ds_write_b32 v2, v64 offset:0
	ds_write_b32 v2, v65 offset:8
	ds_write_b32 v2, v66 offset:16
	ds_write_b32 v2, v67 offset:24
	ds_write_b32 v2, v68 offset:32
	ds_write_b32 v2, v69 offset:40
	ds_write_b32 v2, v70 offset:48
	ds_write_b32 v2, v71 offset:56
	ds_write_b32 v2, v72 offset:64
	ds_write_b32 v2, v73 offset:72
	ds_write_b32 v2, v74 offset:80
	ds_write_b32 v2, v75 offset:88
	ds_write_b32 v2, v76 offset:96
	ds_write_b32 v2, v77 offset:104
	ds_write_b32 v2, v78 offset:112
	ds_write_b32 v2, v79 offset:120
	ds_write_b32 v2, v80 offset:128
	ds_write_b32 v2, v81 offset:136
	ds_write_b32 v2, v82 offset:144
	ds_write_b32 v2, v83 offset:152
	ds_write_b32 v2, v84 offset:160
	ds_write_b32 v2, v85 offset:168
	ds_write_b32 v2, v86 offset:176
	ds_write_b32 v2, v87 offset:184
	ds_write_b32 v2, v88 offset:192
	ds_write_b32 v2, v89 offset:200
	ds_write_b32 v2, v90 offset:208
	ds_write_b32 v2, v91 offset:216
	ds_write_b32 v2, v92 offset:224
	ds_write_b32 v2, v93 offset:232
	ds_write_b32 v2, v94 offset:240
	ds_write_b32 v2, v95 offset:248
	s_lshr_b32 s70, s67, 2
	s_lshl_b32 s70, s70, 8
	s_and_b32 s71, s67, 3
	s_lshl_b32 s71, s71, 5
	s_add_i32 s70, s70, s71
	s_add_i32 s70, s70, s40
	s_lshl_b32 s70, s70, 12
	s_lshl_b32 s71, s55, 7
	s_add_i32 s70, s70, s71
	s_add_u32 s70, s70, 0x2200000
	s_add_u32 s70, s26, s70
	s_addc_u32 s71, s27, 0
	s_waitcnt lgkmcnt(0)
	ds_read_b64 v[160:161], v3 offset:0
	ds_read_b64 v[162:163], v3 offset:8
	ds_read_b64 v[164:165], v3 offset:16
	ds_read_b64 v[166:167], v3 offset:24
	ds_read_b64 v[168:169], v3 offset:2112
	ds_read_b64 v[170:171], v3 offset:2120
	ds_read_b64 v[172:173], v3 offset:2128
	ds_read_b64 v[174:175], v3 offset:2136
	ds_read_b64 v[176:177], v3 offset:4224
	ds_read_b64 v[178:179], v3 offset:4232
	ds_read_b64 v[180:181], v3 offset:4240
	ds_read_b64 v[182:183], v3 offset:4248
	ds_read_b64 v[184:185], v3 offset:6336
	ds_read_b64 v[186:187], v3 offset:6344
	ds_read_b64 v[188:189], v3 offset:6352
	ds_read_b64 v[190:191], v3 offset:6360
	s_waitcnt lgkmcnt(12)
	v_mul_f32_e32 v160, v160, v104
	v_mul_f32_e32 v161, v161, v105
	v_mul_f32_e32 v162, v162, v106
	v_mul_f32_e32 v163, v163, v107
	v_mul_f32_e32 v164, v164, v108
	v_mul_f32_e32 v165, v165, v109
	v_mul_f32_e32 v166, v166, v110
	v_mul_f32_e32 v167, v167, v111
	v_cvt_pk_bf16_f32 v192, v160, v161
	v_cvt_pk_bf16_f32 v193, v162, v163
	v_cvt_pk_bf16_f32 v194, v164, v165
	v_cvt_pk_bf16_f32 v195, v166, v167
	v_mov_b32_e32 v9, v4
	global_store_dwordx4 v9, v[192:195], s[70:71]
	s_waitcnt lgkmcnt(8)
	v_mul_f32_e32 v168, v168, v104
	v_mul_f32_e32 v169, v169, v105
	v_mul_f32_e32 v170, v170, v106
	v_mul_f32_e32 v171, v171, v107
	v_mul_f32_e32 v172, v172, v108
	v_mul_f32_e32 v173, v173, v109
	v_mul_f32_e32 v174, v174, v110
	v_mul_f32_e32 v175, v175, v111
	v_cvt_pk_bf16_f32 v196, v168, v169
	v_cvt_pk_bf16_f32 v197, v170, v171
	v_cvt_pk_bf16_f32 v198, v172, v173
	v_cvt_pk_bf16_f32 v199, v174, v175
	v_add_u32_e32 v9, 0x8000, v9
	global_store_dwordx4 v9, v[196:199], s[70:71]
	s_waitcnt lgkmcnt(4)
	v_mul_f32_e32 v176, v176, v104
	v_mul_f32_e32 v177, v177, v105
	v_mul_f32_e32 v178, v178, v106
	v_mul_f32_e32 v179, v179, v107
	v_mul_f32_e32 v180, v180, v108
	v_mul_f32_e32 v181, v181, v109
	v_mul_f32_e32 v182, v182, v110
	v_mul_f32_e32 v183, v183, v111
	v_cvt_pk_bf16_f32 v200, v176, v177
	v_cvt_pk_bf16_f32 v201, v178, v179
	v_cvt_pk_bf16_f32 v202, v180, v181
	v_cvt_pk_bf16_f32 v203, v182, v183
	v_add_u32_e32 v9, 0x8000, v9
	global_store_dwordx4 v9, v[200:203], s[70:71]
	s_waitcnt lgkmcnt(0)
	v_mul_f32_e32 v184, v184, v104
	v_mul_f32_e32 v185, v185, v105
	v_mul_f32_e32 v186, v186, v106
	v_mul_f32_e32 v187, v187, v107
	v_mul_f32_e32 v188, v188, v108
	v_mul_f32_e32 v189, v189, v109
	v_mul_f32_e32 v190, v190, v110
	v_mul_f32_e32 v191, v191, v111
	v_cvt_pk_bf16_f32 v204, v184, v185
	v_cvt_pk_bf16_f32 v205, v186, v187
	v_cvt_pk_bf16_f32 v206, v188, v189
	v_cvt_pk_bf16_f32 v207, v190, v191
	v_add_u32_e32 v9, 0x8000, v9
	global_store_dwordx4 v9, v[204:207], s[70:71]
	s_waitcnt vmcnt(0) lgkmcnt(0)
